# grid-barrier poll: 16 counter loads issued back-to-back with one wait (was 12 serial round trips), same final register state
# speedup vs baseline: 1.0075x; 1.0005x over previous
; DEVI unsigned xb_ld(unsigned* p) { return __hip_atomic_load(p, __ATOMIC_RELAXED, __HIP_MEMORY_SCOPE_AGENT); }
; DEVI void xcd_barrier_complete(unsigned* bar, unsigned x, unsigned& nloc, unsigned& nx) {
;     ...
;   for (;;) {
;     sum = 0u; cnt = 0u; mine = 0u;
; #pragma unroll
;     for (unsigned j = 0; j < 16; ++j) { const unsigned c = xb_ld(&bar[XB_XCNT(j)]); sum += c; cnt += (c > 0u) ? 1u : 0u; mine = (j == x) ? c : mine; }
;     if (sum == G) break;
;     __builtin_amdgcn_s_sleep(1);
;     if ((++sp & 255u) == 0u) { if (xb_ld(&bar[XB_TMO])) break; if (sp > XB_SPIN_CAP) { atomicAdd(&bar[XB_TMO], 1u); break; } }
;   }
.LBB0_76:
	v_mov_b64_e32 v[12:13], s[22:23]
	flat_load_dword v2, v[12:13] offset:1024 sc1
	s_waitcnt lgkmcnt(0)
	flat_load_dword v0, v[12:13] offset:1280 sc1
	flat_load_dword v3, v[12:13] offset:1536 sc1
	s_or_b64 s[18:19], s[18:19], exec
	s_or_b64 s[16:17], s[16:17], exec
	flat_load_dword v4, v[12:13] offset:1792 sc1
	flat_load_dword v5, v[12:13] offset:2048 sc1
	flat_load_dword v6, v[12:13] offset:2304 sc1
	flat_load_dword v7, v[12:13] offset:2560 sc1
	flat_load_dword v8, v[12:13] offset:2816 sc1
	flat_load_dword v9, v[12:13] offset:3072 sc1
	flat_load_dword v10, v[12:13] offset:3328 sc1
	flat_load_dword v11, v[12:13] offset:3584 sc1
	flat_load_dword v12, v[12:13] offset:3840 sc1
	v_mov_b64_e32 v[14:15], s[24:25]
	flat_load_dword v13, v[14:15] sc1
	v_mov_b64_e32 v[14:15], s[26:27]
	flat_load_dword v14, v[14:15] sc1
	v_mov_b64_e32 v[16:17], s[28:29]
	flat_load_dword v15, v[16:17] sc1
	v_mov_b64_e32 v[16:17], s[30:31]
	flat_load_dword v16, v[16:17] sc1
	s_waitcnt vmcnt(0) lgkmcnt(0)
	v_add3_u32 v18, v2, v0, v3
	v_add3_u32 v18, v18, v4, v5
	v_add3_u32 v18, v18, v6, v7
	v_add3_u32 v18, v18, v8, v9
	v_add3_u32 v18, v18, v10, v11
	v_add3_u32 v18, v18, v12, v13
	v_add3_u32 v18, v18, v14, v15
	v_add_u32_e32 v17, v18, v16
	v_cmp_ne_u32_e32 vcc, s5, v17
	s_and_saveexec_b64 s[36:37], vcc
	s_cbranch_execz .LBB0_75
	s_and_b32 s6, s50, 0xff
	s_mov_b64 s[38:39], -1
	s_cmp_eq_u32 s6, 0
	s_mov_b64 s[42:43], -1
	s_mov_b64 s[40:41], -1
	s_sleep 1
	s_cbranch_scc1 .LBB0_79
	s_and_saveexec_b64 s[6:7], s[42:43]
	s_cbranch_execz .LBB0_74
	s_branch .LBB0_82

; DEVI unsigned xb_ld(unsigned* p) { return __hip_atomic_load(p, __ATOMIC_RELAXED, __HIP_MEMORY_SCOPE_AGENT); }
; DEVI void xcd_barrier_complete(unsigned* bar, unsigned x, unsigned& nloc, unsigned& nx) {
;     ...
;   for (;;) {
;     sum = 0u; cnt = 0u; mine = 0u;
; #pragma unroll
;     for (unsigned j = 0; j < 16; ++j) { const unsigned c = xb_ld(&bar[XB_XCNT(j)]); sum += c; cnt += (c > 0u) ? 1u : 0u; mine = (j == x) ? c : mine; }
;     if (sum == G) break;
;     __builtin_amdgcn_s_sleep(1);
;     if ((++sp & 255u) == 0u) { if (xb_ld(&bar[XB_TMO])) break; if (sp > XB_SPIN_CAP) { atomicAdd(&bar[XB_TMO], 1u); break; } }
;   }
.LBB0_1442:
	v_mov_b64_e32 v[12:13], s[22:23]
	flat_load_dword v2, v[12:13] offset:1024 sc1
	s_waitcnt lgkmcnt(0)
	flat_load_dword v0, v[12:13] offset:1280 sc1
	flat_load_dword v3, v[12:13] offset:1536 sc1
	s_or_b64 s[18:19], s[18:19], exec
	s_or_b64 s[16:17], s[16:17], exec
	flat_load_dword v4, v[12:13] offset:1792 sc1
	flat_load_dword v5, v[12:13] offset:2048 sc1
	flat_load_dword v6, v[12:13] offset:2304 sc1
	flat_load_dword v7, v[12:13] offset:2560 sc1
	flat_load_dword v8, v[12:13] offset:2816 sc1
	flat_load_dword v9, v[12:13] offset:3072 sc1
	flat_load_dword v10, v[12:13] offset:3328 sc1
	flat_load_dword v11, v[12:13] offset:3584 sc1
	flat_load_dword v12, v[12:13] offset:3840 sc1
	v_mov_b64_e32 v[14:15], s[24:25]
	flat_load_dword v13, v[14:15] sc1
	v_mov_b64_e32 v[14:15], s[26:27]
	flat_load_dword v14, v[14:15] sc1
	v_mov_b64_e32 v[16:17], s[28:29]
	flat_load_dword v15, v[16:17] sc1
	v_mov_b64_e32 v[16:17], s[30:31]
	flat_load_dword v16, v[16:17] sc1
	s_waitcnt vmcnt(0) lgkmcnt(0)
	v_add3_u32 v18, v2, v0, v3
	v_add3_u32 v18, v18, v4, v5
	v_add3_u32 v18, v18, v6, v7
	v_add3_u32 v18, v18, v8, v9
	v_add3_u32 v18, v18, v10, v11
	v_add3_u32 v18, v18, v12, v13
	v_add3_u32 v18, v18, v14, v15
	v_add_u32_e32 v17, v18, v16
	v_cmp_ne_u32_e32 vcc, s5, v17
	s_and_saveexec_b64 s[38:39], vcc
	s_cbranch_execz .LBB0_1441
	s_and_b32 s6, s52, 0xff
	s_mov_b64 s[40:41], -1
	s_cmp_eq_u32 s6, 0
	s_mov_b64 s[42:43], -1
	s_mov_b64 s[50:51], -1
	s_sleep 1
	s_cbranch_scc1 .LBB0_1445
	s_and_saveexec_b64 s[6:7], s[42:43]
	s_cbranch_execz .LBB0_1440
	s_branch .LBB0_1448

; DEVI unsigned xb_ld(unsigned* p) { return __hip_atomic_load(p, __ATOMIC_RELAXED, __HIP_MEMORY_SCOPE_AGENT); }
; DEVI void xcd_barrier_complete(unsigned* bar, unsigned x, unsigned& nloc, unsigned& nx) {
;     ...
;   for (;;) {
;     sum = 0u; cnt = 0u; mine = 0u;
; #pragma unroll
;     for (unsigned j = 0; j < 16; ++j) { const unsigned c = xb_ld(&bar[XB_XCNT(j)]); sum += c; cnt += (c > 0u) ? 1u : 0u; mine = (j == x) ? c : mine; }
;     if (sum == G) break;
;     __builtin_amdgcn_s_sleep(1);
;     if ((++sp & 255u) == 0u) { if (xb_ld(&bar[XB_TMO])) break; if (sp > XB_SPIN_CAP) { atomicAdd(&bar[XB_TMO], 1u); break; } }
;   }
.LBB0_1523:
	v_mov_b64_e32 v[12:13], s[22:23]
	flat_load_dword v2, v[12:13] offset:1024 sc1
	s_waitcnt lgkmcnt(0)
	flat_load_dword v0, v[12:13] offset:1280 sc1
	flat_load_dword v3, v[12:13] offset:1536 sc1
	s_or_b64 s[38:39], s[38:39], exec
	s_or_b64 s[36:37], s[36:37], exec
	flat_load_dword v4, v[12:13] offset:1792 sc1
	flat_load_dword v5, v[12:13] offset:2048 sc1
	flat_load_dword v6, v[12:13] offset:2304 sc1
	flat_load_dword v7, v[12:13] offset:2560 sc1
	flat_load_dword v8, v[12:13] offset:2816 sc1
	flat_load_dword v9, v[12:13] offset:3072 sc1
	flat_load_dword v10, v[12:13] offset:3328 sc1
	flat_load_dword v11, v[12:13] offset:3584 sc1
	flat_load_dword v12, v[12:13] offset:3840 sc1
	v_mov_b64_e32 v[14:15], s[24:25]
	flat_load_dword v13, v[14:15] sc1
	v_mov_b64_e32 v[14:15], s[26:27]
	flat_load_dword v14, v[14:15] sc1
	v_mov_b64_e32 v[16:17], s[28:29]
	flat_load_dword v15, v[16:17] sc1
	v_mov_b64_e32 v[16:17], s[30:31]
	flat_load_dword v16, v[16:17] sc1
	s_waitcnt vmcnt(0) lgkmcnt(0)
	v_add3_u32 v18, v2, v0, v3
	v_add3_u32 v18, v18, v4, v5
	v_add3_u32 v18, v18, v6, v7
	v_add3_u32 v18, v18, v8, v9
	v_add3_u32 v18, v18, v10, v11
	v_add3_u32 v18, v18, v12, v13
	v_add3_u32 v18, v18, v14, v15
	v_add_u32_e32 v17, v18, v16
	v_cmp_ne_u32_e32 vcc, s5, v17
	s_and_saveexec_b64 s[40:41], vcc
	s_cbranch_execz .LBB0_1522
	s_and_b32 s6, s13, 0xff
	s_mov_b64 s[50:51], -1
	s_cmp_eq_u32 s6, 0
	s_mov_b64 s[42:43], -1
	s_mov_b64 s[52:53], -1
	s_sleep 1
	s_cbranch_scc1 .LBB0_1526
	s_and_saveexec_b64 s[6:7], s[42:43]
	s_cbranch_execz .LBB0_1521
	s_branch .LBB0_1529

; DEVI unsigned xb_ld(unsigned* p) { return __hip_atomic_load(p, __ATOMIC_RELAXED, __HIP_MEMORY_SCOPE_AGENT); }
; DEVI void xcd_barrier_complete(unsigned* bar, unsigned x, unsigned& nloc, unsigned& nx) {
;     ...
;   for (;;) {
;     sum = 0u; cnt = 0u; mine = 0u;
; #pragma unroll
;     for (unsigned j = 0; j < 16; ++j) { const unsigned c = xb_ld(&bar[XB_XCNT(j)]); sum += c; cnt += (c > 0u) ? 1u : 0u; mine = (j == x) ? c : mine; }
;     if (sum == G) break;
;     __builtin_amdgcn_s_sleep(1);
;     if ((++sp & 255u) == 0u) { if (xb_ld(&bar[XB_TMO])) break; if (sp > XB_SPIN_CAP) { atomicAdd(&bar[XB_TMO], 1u); break; } }
;   }
.LBB0_1572:
	v_mov_b64_e32 v[12:13], s[22:23]
	flat_load_dword v2, v[12:13] offset:1024 sc1
	s_waitcnt lgkmcnt(0)
	flat_load_dword v0, v[12:13] offset:1280 sc1
	flat_load_dword v3, v[12:13] offset:1536 sc1
	s_or_b64 s[50:51], s[50:51], exec
	s_or_b64 s[40:41], s[40:41], exec
	flat_load_dword v4, v[12:13] offset:1792 sc1
	flat_load_dword v5, v[12:13] offset:2048 sc1
	flat_load_dword v6, v[12:13] offset:2304 sc1
	flat_load_dword v7, v[12:13] offset:2560 sc1
	flat_load_dword v8, v[12:13] offset:2816 sc1
	flat_load_dword v9, v[12:13] offset:3072 sc1
	flat_load_dword v10, v[12:13] offset:3328 sc1
	flat_load_dword v11, v[12:13] offset:3584 sc1
	flat_load_dword v12, v[12:13] offset:3840 sc1
	v_mov_b64_e32 v[14:15], s[24:25]
	flat_load_dword v13, v[14:15] sc1
	v_mov_b64_e32 v[14:15], s[26:27]
	flat_load_dword v14, v[14:15] sc1
	v_mov_b64_e32 v[16:17], s[28:29]
	flat_load_dword v15, v[16:17] sc1
	v_mov_b64_e32 v[16:17], s[30:31]
	flat_load_dword v16, v[16:17] sc1
	s_waitcnt vmcnt(0) lgkmcnt(0)
	v_add3_u32 v18, v2, v0, v3
	v_add3_u32 v18, v18, v4, v5
	v_add3_u32 v18, v18, v6, v7
	v_add3_u32 v18, v18, v8, v9
	v_add3_u32 v18, v18, v10, v11
	v_add3_u32 v18, v18, v12, v13
	v_add3_u32 v18, v18, v14, v15
	v_add_u32_e32 v17, v18, v16
	v_cmp_ne_u32_e32 vcc, s5, v17
	s_and_saveexec_b64 s[52:53], vcc
	s_cbranch_execz .LBB0_1571
	s_and_b32 s6, s13, 0xff
	s_mov_b64 s[54:55], -1
	s_cmp_eq_u32 s6, 0
	s_mov_b64 s[42:43], -1
	s_mov_b64 s[94:95], -1
	s_sleep 1
	s_cbranch_scc1 .LBB0_1575
	s_and_saveexec_b64 s[6:7], s[42:43]
	s_cbranch_execz .LBB0_1570
	s_branch .LBB0_1578

; DEVI unsigned xb_ld(unsigned* p) { return __hip_atomic_load(p, __ATOMIC_RELAXED, __HIP_MEMORY_SCOPE_AGENT); }
; DEVI void xcd_barrier_complete(unsigned* bar, unsigned x, unsigned& nloc, unsigned& nx) {
;     ...
;   for (;;) {
;     sum = 0u; cnt = 0u; mine = 0u;
; #pragma unroll
;     for (unsigned j = 0; j < 16; ++j) { const unsigned c = xb_ld(&bar[XB_XCNT(j)]); sum += c; cnt += (c > 0u) ? 1u : 0u; mine = (j == x) ? c : mine; }
;     if (sum == G) break;
;     __builtin_amdgcn_s_sleep(1);
;     if ((++sp & 255u) == 0u) { if (xb_ld(&bar[XB_TMO])) break; if (sp > XB_SPIN_CAP) { atomicAdd(&bar[XB_TMO], 1u); break; } }
;   }
.LBB0_1623:
	v_mov_b64_e32 v[12:13], s[22:23]
	flat_load_dword v2, v[12:13] offset:1024 sc1
	s_waitcnt lgkmcnt(0)
	flat_load_dword v0, v[12:13] offset:1280 sc1
	flat_load_dword v3, v[12:13] offset:1536 sc1
	s_or_b64 s[52:53], s[52:53], exec
	s_or_b64 s[50:51], s[50:51], exec
	flat_load_dword v4, v[12:13] offset:1792 sc1
	flat_load_dword v5, v[12:13] offset:2048 sc1
	flat_load_dword v6, v[12:13] offset:2304 sc1
	flat_load_dword v7, v[12:13] offset:2560 sc1
	flat_load_dword v8, v[12:13] offset:2816 sc1
	flat_load_dword v9, v[12:13] offset:3072 sc1
	flat_load_dword v10, v[12:13] offset:3328 sc1
	flat_load_dword v11, v[12:13] offset:3584 sc1
	flat_load_dword v12, v[12:13] offset:3840 sc1
	v_mov_b64_e32 v[14:15], s[24:25]
	flat_load_dword v13, v[14:15] sc1
	v_mov_b64_e32 v[14:15], s[26:27]
	flat_load_dword v14, v[14:15] sc1
	v_mov_b64_e32 v[16:17], s[28:29]
	flat_load_dword v15, v[16:17] sc1
	v_mov_b64_e32 v[16:17], s[30:31]
	flat_load_dword v16, v[16:17] sc1
	s_waitcnt vmcnt(0) lgkmcnt(0)
	v_add3_u32 v18, v2, v0, v3
	v_add3_u32 v18, v18, v4, v5
	v_add3_u32 v18, v18, v6, v7
	v_add3_u32 v18, v18, v8, v9
	v_add3_u32 v18, v18, v10, v11
	v_add3_u32 v18, v18, v12, v13
	v_add3_u32 v18, v18, v14, v15
	v_add_u32_e32 v17, v18, v16
	v_cmp_ne_u32_e32 vcc, s5, v17
	s_and_saveexec_b64 s[54:55], vcc
	s_cbranch_execz .LBB0_1622
	s_and_b32 s6, s13, 0xff
	s_mov_b64 s[94:95], -1
	s_cmp_eq_u32 s6, 0
	s_mov_b64 s[6:7], -1
	s_mov_b64 s[42:43], -1
	s_sleep 1
	s_cbranch_scc1 .LBB0_1626
	s_and_saveexec_b64 s[82:83], s[6:7]
	s_cbranch_execz .LBB0_1621
	s_branch .LBB0_1629

; DEVI unsigned xb_ld(unsigned* p) { return __hip_atomic_load(p, __ATOMIC_RELAXED, __HIP_MEMORY_SCOPE_AGENT); }
; DEVI void xcd_barrier_complete(unsigned* bar, unsigned x, unsigned& nloc, unsigned& nx) {
;     ...
;   for (;;) {
;     sum = 0u; cnt = 0u; mine = 0u;
; #pragma unroll
;     for (unsigned j = 0; j < 16; ++j) { const unsigned c = xb_ld(&bar[XB_XCNT(j)]); sum += c; cnt += (c > 0u) ? 1u : 0u; mine = (j == x) ? c : mine; }
;     if (sum == G) break;
;     __builtin_amdgcn_s_sleep(1);
;     if ((++sp & 255u) == 0u) { if (xb_ld(&bar[XB_TMO])) break; if (sp > XB_SPIN_CAP) { atomicAdd(&bar[XB_TMO], 1u); break; } }
;   }
.LBB0_1771:
	v_mov_b64_e32 v[12:13], s[22:23]
	flat_load_dword v2, v[12:13] offset:1024 sc1
	s_waitcnt lgkmcnt(0)
	flat_load_dword v0, v[12:13] offset:1280 sc1
	flat_load_dword v3, v[12:13] offset:1536 sc1
	s_or_b64 s[50:51], s[50:51], exec
	s_or_b64 s[40:41], s[40:41], exec
	flat_load_dword v4, v[12:13] offset:1792 sc1
	flat_load_dword v5, v[12:13] offset:2048 sc1
	flat_load_dword v6, v[12:13] offset:2304 sc1
	flat_load_dword v7, v[12:13] offset:2560 sc1
	flat_load_dword v8, v[12:13] offset:2816 sc1
	flat_load_dword v9, v[12:13] offset:3072 sc1
	flat_load_dword v10, v[12:13] offset:3328 sc1
	flat_load_dword v11, v[12:13] offset:3584 sc1
	flat_load_dword v12, v[12:13] offset:3840 sc1
	v_mov_b64_e32 v[14:15], s[24:25]
	flat_load_dword v13, v[14:15] sc1
	v_mov_b64_e32 v[14:15], s[26:27]
	flat_load_dword v14, v[14:15] sc1
	v_mov_b64_e32 v[16:17], s[28:29]
	flat_load_dword v15, v[16:17] sc1
	v_mov_b64_e32 v[16:17], s[30:31]
	flat_load_dword v16, v[16:17] sc1
	s_waitcnt vmcnt(0) lgkmcnt(0)
	v_add3_u32 v18, v2, v0, v3
	v_add3_u32 v18, v18, v4, v5
	v_add3_u32 v18, v18, v6, v7
	v_add3_u32 v18, v18, v8, v9
	v_add3_u32 v18, v18, v10, v11
	v_add3_u32 v18, v18, v12, v13
	v_add3_u32 v18, v18, v14, v15
	v_add_u32_e32 v17, v18, v16
	v_cmp_ne_u32_e32 vcc, s5, v17
	s_and_saveexec_b64 s[52:53], vcc
	s_cbranch_execz .LBB0_1770
	s_and_b32 s6, s13, 0xff
	s_mov_b64 s[54:55], -1
	s_cmp_eq_u32 s6, 0
	s_mov_b64 s[6:7], -1
	s_mov_b64 s[42:43], -1
	s_sleep 1
	s_cbranch_scc1 .LBB0_1774
	s_and_saveexec_b64 s[82:83], s[6:7]
	s_cbranch_execz .LBB0_1769
	s_branch .LBB0_1777

; DEVI unsigned xb_ld(unsigned* p) { return __hip_atomic_load(p, __ATOMIC_RELAXED, __HIP_MEMORY_SCOPE_AGENT); }
; DEVI void xcd_barrier_complete(unsigned* bar, unsigned x, unsigned& nloc, unsigned& nx) {
;     ...
;   for (;;) {
;     sum = 0u; cnt = 0u; mine = 0u;
; #pragma unroll
;     for (unsigned j = 0; j < 16; ++j) { const unsigned c = xb_ld(&bar[XB_XCNT(j)]); sum += c; cnt += (c > 0u) ? 1u : 0u; mine = (j == x) ? c : mine; }
;     if (sum == G) break;
;     __builtin_amdgcn_s_sleep(1);
;     if ((++sp & 255u) == 0u) { if (xb_ld(&bar[XB_TMO])) break; if (sp > XB_SPIN_CAP) { atomicAdd(&bar[XB_TMO], 1u); break; } }
;   }
.LBB0_1952:
	v_mov_b64_e32 v[12:13], s[22:23]
	flat_load_dword v2, v[12:13] offset:1024 sc1
	s_waitcnt lgkmcnt(0)
	flat_load_dword v0, v[12:13] offset:1280 sc1
	flat_load_dword v3, v[12:13] offset:1536 sc1
	s_or_b64 s[18:19], s[18:19], exec
	s_or_b64 s[16:17], s[16:17], exec
	flat_load_dword v4, v[12:13] offset:1792 sc1
	flat_load_dword v5, v[12:13] offset:2048 sc1
	flat_load_dword v6, v[12:13] offset:2304 sc1
	flat_load_dword v7, v[12:13] offset:2560 sc1
	flat_load_dword v8, v[12:13] offset:2816 sc1
	flat_load_dword v9, v[12:13] offset:3072 sc1
	flat_load_dword v10, v[12:13] offset:3328 sc1
	flat_load_dword v11, v[12:13] offset:3584 sc1
	flat_load_dword v12, v[12:13] offset:3840 sc1
	v_mov_b64_e32 v[14:15], s[24:25]
	flat_load_dword v13, v[14:15] sc1
	v_mov_b64_e32 v[14:15], s[26:27]
	flat_load_dword v14, v[14:15] sc1
	v_mov_b64_e32 v[16:17], s[28:29]
	flat_load_dword v15, v[16:17] sc1
	v_mov_b64_e32 v[16:17], s[30:31]
	flat_load_dword v16, v[16:17] sc1
	s_waitcnt vmcnt(0) lgkmcnt(0)
	v_add3_u32 v18, v2, v0, v3
	v_add3_u32 v18, v18, v4, v5
	v_add3_u32 v18, v18, v6, v7
	v_add3_u32 v18, v18, v8, v9
	v_add3_u32 v18, v18, v10, v11
	v_add3_u32 v18, v18, v12, v13
	v_add3_u32 v18, v18, v14, v15
	v_add_u32_e32 v17, v18, v16
	v_cmp_ne_u32_e32 vcc, s5, v17
	s_and_saveexec_b64 s[36:37], vcc
	s_cbranch_execz .LBB0_1951
	s_and_b32 s6, s13, 0xff
	s_mov_b64 s[38:39], -1
	s_cmp_eq_u32 s6, 0
	s_mov_b64 s[6:7], -1
	s_mov_b64 s[40:41], -1
	s_sleep 1
	s_cbranch_scc1 .LBB0_1955
	s_and_saveexec_b64 s[42:43], s[6:7]
	s_cbranch_execz .LBB0_1950
	s_branch .LBB0_1958

; DEVI unsigned xb_ld(unsigned* p) { return __hip_atomic_load(p, __ATOMIC_RELAXED, __HIP_MEMORY_SCOPE_AGENT); }
; DEVI void xcd_barrier_complete(unsigned* bar, unsigned x, unsigned& nloc, unsigned& nx) {
;     ...
;   for (;;) {
;     sum = 0u; cnt = 0u; mine = 0u;
; #pragma unroll
;     for (unsigned j = 0; j < 16; ++j) { const unsigned c = xb_ld(&bar[XB_XCNT(j)]); sum += c; cnt += (c > 0u) ? 1u : 0u; mine = (j == x) ? c : mine; }
;     if (sum == G) break;
;     __builtin_amdgcn_s_sleep(1);
;     if ((++sp & 255u) == 0u) { if (xb_ld(&bar[XB_TMO])) break; if (sp > XB_SPIN_CAP) { atomicAdd(&bar[XB_TMO], 1u); break; } }
;   }
.LBB0_2202:
	v_mov_b64_e32 v[12:13], s[22:23]
	flat_load_dword v2, v[12:13] offset:1024 sc1
	s_waitcnt lgkmcnt(0)
	flat_load_dword v0, v[12:13] offset:1280 sc1
	flat_load_dword v3, v[12:13] offset:1536 sc1
	s_or_b64 s[18:19], s[18:19], exec
	s_or_b64 s[16:17], s[16:17], exec
	flat_load_dword v4, v[12:13] offset:1792 sc1
	flat_load_dword v5, v[12:13] offset:2048 sc1
	flat_load_dword v6, v[12:13] offset:2304 sc1
	flat_load_dword v7, v[12:13] offset:2560 sc1
	flat_load_dword v8, v[12:13] offset:2816 sc1
	flat_load_dword v9, v[12:13] offset:3072 sc1
	flat_load_dword v10, v[12:13] offset:3328 sc1
	flat_load_dword v11, v[12:13] offset:3584 sc1
	flat_load_dword v12, v[12:13] offset:3840 sc1
	v_mov_b64_e32 v[14:15], s[24:25]
	flat_load_dword v13, v[14:15] sc1
	v_mov_b64_e32 v[14:15], s[26:27]
	flat_load_dword v14, v[14:15] sc1
	v_mov_b64_e32 v[16:17], s[28:29]
	flat_load_dword v15, v[16:17] sc1
	v_mov_b64_e32 v[16:17], s[30:31]
	flat_load_dword v16, v[16:17] sc1
	s_waitcnt vmcnt(0) lgkmcnt(0)
	v_add3_u32 v18, v2, v0, v3
	v_add3_u32 v18, v18, v4, v5
	v_add3_u32 v18, v18, v6, v7
	v_add3_u32 v18, v18, v8, v9
	v_add3_u32 v18, v18, v10, v11
	v_add3_u32 v18, v18, v12, v13
	v_add3_u32 v18, v18, v14, v15
	v_add_u32_e32 v17, v18, v16
	v_cmp_ne_u32_e32 vcc, s5, v17
	s_and_saveexec_b64 s[36:37], vcc
	s_cbranch_execz .LBB0_2201
	s_and_b32 s6, s9, 0xff
	s_mov_b64 s[38:39], -1
	s_cmp_eq_u32 s6, 0
	s_mov_b64 s[6:7], -1
	s_mov_b64 s[40:41], -1
	s_sleep 1
	s_cbranch_scc1 .LBB0_2205
	s_and_saveexec_b64 s[42:43], s[6:7]
	s_cbranch_execz .LBB0_2200
	s_branch .LBB0_2208
